# stack on balanced loads: load-segment trim plus gate-merge epilogue first two loads overlapped with the next six (early vmcnt(0) replaced by vmcnt(6) after the loads)
# baseline (speedup 1.0000x reference)
; __device__ __forceinline__ float sigmoid_f(float x) { return __builtin_amdgcn_rcpf(1.0f + __builtin_amdgcn_exp2f(-x * LOG2E)); }
; __device__ __forceinline__ u32x4 pack8(const f32x4 a, const f32x4 b) { u32x4 w; w.x = cvt_pk_bf16(a[0], a[1]); w.y = cvt_pk_bf16(a[2], a[3]); w.z = cvt_pk_bf16(b[0], b[1]); w.w = cvt_pk_bf16(b[2], b[3]); return w; }
; __device__ __forceinline__ void unpack8(const u32x4 w, f32x4& a, f32x4& b) { a = (f32x4){bf_lo(w.x), bf_hi(w.x), bf_lo(w.y), bf_hi(w.y)}; b = (f32x4){bf_lo(w.z), bf_hi(w.z), bf_lo(w.w), bf_hi(w.w)}; }
;     __device__ __forceinline__ void operator()(const Acc& acc, const Unit& u, int wr, int wc, int fr, int fq, const float (&sv8)[8]) const {
;         const int col0 = u.pn * 128 + wc * 32 + 8 * fq, rowb = u.pm * 256 + wr * 64 + fr;
; #pragma unroll
;         for (int ai = 0; ai < 2; ++ai) {
;             u32x4 ar[4], mr[4];
; #pragma unroll
;             for (int m = 0; m < 4; ++m) { const size_t off = (size_t)(rowb + ai * 128 + m * 16) * 2048 + col0; ar[m] = *(const u32x4*)(MRG + off); mr[m] = *(const u32x4*)(MS + off); }
; #pragma unroll
;             for (int m = 0; m < 4; ++m) {
;                 const float rs = rsqrtf(sv8[ai * 4 + m] * (1.0f / DM) + EPS);
;                 f32x4 a0, a1, m0, m1; unpack8(ar[m], a0, a1); unpack8(mr[m], m0, m1);
;                 f32x4 o0, o1;
; #pragma unroll
;                 for (int j = 0; j < 4; ++j) { o0[j] = sigmoid_f(acc[ai][0][m][0][j] * rs) * a0[j] + sigmoid_f(acc[ai][1][m][0][j] * rs) * m0[j];
;                                               o1[j] = sigmoid_f(acc[ai][0][m][1][j] * rs) * a1[j] + sigmoid_f(acc[ai][1][m][1][j] * rs) * m1[j]; }
;                 *(u32x4*)(MRG + (size_t)(rowb + ai * 128 + m * 16) * 2048 + col0) = pack8(o0, o1);
.LBB0_1196:
	v_lshl_or_b32 v152, s57, 7, v222
	v_ashrrev_i32_e32 v209, 31, v208
	v_ashrrev_i32_e32 v153, 31, v152
	v_lshlrev_b64 v[128:129], 11, v[208:209]
	v_lshl_add_u64 v[128:129], v[128:129], 0, v[152:153]
	v_lshlrev_b64 v[128:129], 1, v[128:129]
	v_lshl_add_u64 v[130:131], s[12:13], 0, v[128:129]
	v_lshl_add_u64 v[128:129], s[14:15], 0, v[128:129]
	global_load_dwordx4 v[160:163], v[130:131], off
	global_load_dwordx4 v[164:167], v[128:129], off
	v_or_b32_e32 v158, 16, v208
	v_or_b32_e32 v156, 32, v208
	v_or_b32_e32 v154, 48, v208
	v_ashrrev_i32_e32 v159, 31, v158
	v_ashrrev_i32_e32 v157, 31, v156
	v_fmamk_f32 v134, v235, 0x3a000000, v226
	v_ashrrev_i32_e32 v155, 31, v154
	v_lshlrev_b64 v[128:129], 11, v[158:159]
	v_lshlrev_b64 v[130:131], 11, v[156:157]
	v_mul_f32_e32 v135, 0x4b800000, v134
	v_lshlrev_b64 v[132:133], 11, v[154:155]
	v_cmp_gt_f32_e32 vcc, s56, v134
	v_lshl_add_u64 v[128:129], v[128:129], 0, v[152:153]
	v_lshl_add_u64 v[130:131], v[130:131], 0, v[152:153]
	v_cndmask_b32_e32 v134, v134, v135, vcc
	v_lshl_add_u64 v[132:133], v[132:133], 0, v[152:153]
	v_lshlrev_b64 v[128:129], 1, v[128:129]
	v_lshlrev_b64 v[130:131], 1, v[130:131]
	v_rsq_f32_e32 v172, v134
	v_lshlrev_b64 v[132:133], 1, v[132:133]
	v_lshl_add_u64 v[134:135], s[12:13], 0, v[128:129]
	v_lshl_add_u64 v[128:129], s[14:15], 0, v[128:129]
	v_lshl_add_u64 v[136:137], s[12:13], 0, v[130:131]
	v_lshl_add_u64 v[130:131], s[14:15], 0, v[130:131]
	v_lshl_add_u64 v[168:169], s[12:13], 0, v[132:133]
	v_lshl_add_u64 v[170:171], s[14:15], 0, v[132:133]
	global_load_dwordx4 v[148:151], v[134:135], off
	global_load_dwordx4 v[144:147], v[128:129], off
	global_load_dwordx4 v[140:143], v[136:137], off
	s_nop 0
	global_load_dwordx4 v[136:139], v[130:131], off
	global_load_dwordx4 v[132:135], v[168:169], off
	s_nop 0
	global_load_dwordx4 v[128:131], v[170:171], off
	s_waitcnt vmcnt(6)
	v_mul_f32_e32 v168, 0x45800000, v172
	v_cndmask_b32_e32 v172, v172, v168, vcc
	v_mul_f32_e32 v120, v120, v172
	v_mul_f32_e32 v121, v121, v172
	v_mul_f32_e32 v124, v124, v172
	v_mul_f32_e32 v116, v116, v172
	v_mul_f32_e32 v125, v125, v172
	v_mul_f32_e32 v117, v117, v172
	v_mul_f32_e32 v120, 0xbfb8aa3b, v120
	v_mul_f32_e32 v121, 0xbfb8aa3b, v121
	v_mul_f32_e32 v112, v112, v172
	v_mul_f32_e32 v124, 0xbfb8aa3b, v124
	v_mul_f32_e32 v116, 0xbfb8aa3b, v116
	v_mul_f32_e32 v125, 0xbfb8aa3b, v125
	v_mul_f32_e32 v117, 0xbfb8aa3b, v117
	v_exp_f32_e32 v120, v120
	v_exp_f32_e32 v121, v121
	v_mul_f32_e32 v112, 0xbfb8aa3b, v112
	v_exp_f32_e32 v124, v124
	v_exp_f32_e32 v116, v116
	v_exp_f32_e32 v125, v125
	v_exp_f32_e32 v117, v117
	v_exp_f32_e32 v112, v112
	v_mul_f32_e32 v113, v113, v172
	v_mul_f32_e32 v113, 0xbfb8aa3b, v113
	v_add_f32_e32 v120, 1.0, v120
	v_add_f32_e32 v121, 1.0, v121
	v_exp_f32_e32 v173, v113
	v_add_f32_e32 v113, 1.0, v124
	v_add_f32_e32 v124, 1.0, v116
	v_add_f32_e32 v125, 1.0, v125
	v_add_f32_e32 v169, 1.0, v117
	v_rcp_f32_e32 v116, v120
	v_rcp_f32_e32 v117, v121
	v_add_f32_e32 v168, 1.0, v112
	v_rcp_f32_e32 v112, v113
	v_rcp_f32_e32 v113, v125
	v_rcp_f32_e32 v120, v124
	v_rcp_f32_e32 v124, v168
	v_rcp_f32_e32 v121, v169
	v_mul_f32_e32 v122, v122, v172
	v_mul_f32_e32 v123, v123, v172
	v_mul_f32_e32 v122, 0xbfb8aa3b, v122
	v_mul_f32_e32 v123, 0xbfb8aa3b, v123
	v_exp_f32_e32 v122, v122
	v_exp_f32_e32 v123, v123
	v_mul_f32_e32 v126, v126, v172
	v_mul_f32_e32 v126, 0xbfb8aa3b, v126
	v_exp_f32_e32 v126, v126
	v_add_f32_e32 v123, 1.0, v123
	v_rcp_f32_e32 v123, v123
	v_lshlrev_b32_e32 v168, 16, v160
	v_lshlrev_b32_e32 v170, 16, v164
	v_and_b32_e32 v171, 0xffff0000, v164
	v_and_b32_e32 v169, 0xffff0000, v160
	v_pk_mul_f32 v[116:117], v[116:117], v[170:171]
	v_mul_f32_e32 v118, v118, v172
	v_pk_fma_f32 v[112:113], v[112:113], v[168:169], v[116:117]
	v_add_f32_e32 v116, 1.0, v173
	v_rcp_f32_e32 v125, v116
	v_lshlrev_b32_e32 v168, 16, v166
	v_and_b32_e32 v169, 0xffff0000, v166
	v_lshlrev_b32_e32 v116, 16, v162
	v_and_b32_e32 v117, 0xffff0000, v162
	v_pk_mul_f32 v[124:125], v[124:125], v[168:169]
	v_mul_f32_e32 v114, v114, v172
	v_pk_fma_f32 v[116:117], v[120:121], v[116:117], v[124:125]
	v_add_f32_e32 v121, 1.0, v122
	v_rcp_f32_e32 v122, v121
	v_mul_f32_e32 v121, v127, v172
	v_mul_f32_e32 v121, 0xbfb8aa3b, v121
	v_mul_f32_e32 v119, v119, v172
	v_mul_f32_e32 v115, v115, v172
	v_add_f32_e32 v120, 1.0, v126
	v_mul_f32_e32 v118, 0xbfb8aa3b, v118
	v_mul_f32_e32 v114, 0xbfb8aa3b, v114
	v_exp_f32_e32 v121, v121
	v_lshlrev_b32_e32 v126, 16, v165
	v_and_b32_e32 v127, 0xffff0000, v165
	v_mul_f32_e32 v119, 0xbfb8aa3b, v119
	v_mul_f32_e32 v115, 0xbfb8aa3b, v115
	v_exp_f32_e32 v118, v118
	v_exp_f32_e32 v124, v114
	v_pk_mul_f32 v[122:123], v[122:123], v[126:127]
	v_exp_f32_e32 v119, v119
	v_exp_f32_e32 v126, v115
	v_add_f32_e32 v121, 1.0, v121
	v_rcp_f32_e32 v120, v120
	v_add_f32_e32 v114, 1.0, v118
	v_add_f32_e32 v118, 1.0, v124
	v_rcp_f32_e32 v121, v121
	v_add_f32_e32 v115, 1.0, v119
	v_add_f32_e32 v119, 1.0, v126
	v_rcp_f32_e32 v118, v118
	v_rcp_f32_e32 v119, v119
	v_rcp_f32_e32 v114, v114
	v_rcp_f32_e32 v115, v115
	v_lshlrev_b32_e32 v124, 16, v161
	v_and_b32_e32 v125, 0xffff0000, v161
	v_pk_fma_f32 v[120:121], v[120:121], v[124:125], v[122:123]
	v_lshlrev_b32_e32 v124, 16, v167
	v_and_b32_e32 v125, 0xffff0000, v167
	v_lshlrev_b32_e32 v122, 16, v163
	v_and_b32_e32 v123, 0xffff0000, v163
	v_pk_mul_f32 v[118:119], v[118:119], v[124:125]
	v_cvt_pk_bf16_f32 v116, v116, v117
	v_pk_fma_f32 v[118:119], v[114:115], v[122:123], v[118:119]
	v_cvt_pk_bf16_f32 v115, v120, v121
	v_cvt_pk_bf16_f32 v117, v118, v119
	v_fmamk_f32 v118, v233, 0x3a000000, v226
	v_mul_f32_e32 v119, 0x4b800000, v118
	v_cmp_gt_f32_e32 vcc, s56, v118
	v_cvt_pk_bf16_f32 v114, v112, v113
	v_lshlrev_b64 v[112:113], 12, v[208:209]
	v_cndmask_b32_e32 v118, v118, v119, vcc
	v_rsq_f32_e32 v120, v118
	v_lshl_add_u64 v[118:119], s[12:13], 0, v[112:113]
	v_lshlrev_b64 v[112:113], 1, v[152:153]
	v_lshl_add_u64 v[118:119], v[118:119], 0, v[112:113]
	v_mul_f32_e32 v121, 0x45800000, v120
	v_cndmask_b32_e32 v120, v120, v121, vcc
	v_mul_f32_e32 v100, v100, v120
	v_mul_f32_e32 v96, v96, v120
	v_mul_f32_e32 v100, 0xbfb8aa3b, v100
	v_mul_f32_e32 v96, 0xbfb8aa3b, v96
	global_store_dwordx4 v[118:119], v[114:117], off
	v_exp_f32_e32 v100, v100
	v_mul_f32_e32 v108, v108, v120
	v_exp_f32_e32 v114, v96
	v_mul_f32_e32 v104, v104, v120
	v_mul_f32_e32 v109, v109, v120
	v_mul_f32_e32 v105, v105, v120
	v_mul_f32_e32 v108, 0xbfb8aa3b, v108
	v_mul_f32_e32 v104, 0xbfb8aa3b, v104
	v_mul_f32_e32 v109, 0xbfb8aa3b, v109
	v_mul_f32_e32 v105, 0xbfb8aa3b, v105
	v_exp_f32_e32 v108, v108
	v_exp_f32_e32 v121, v104
	v_add_f32_e32 v96, 1.0, v100
	v_add_f32_e32 v100, 1.0, v114
	v_exp_f32_e32 v109, v109
	v_exp_f32_e32 v114, v105
	v_add_f32_e32 v104, 1.0, v108
	v_add_f32_e32 v108, 1.0, v121
	v_add_f32_e32 v105, 1.0, v109
	v_add_f32_e32 v109, 1.0, v114
	v_rcp_f32_e32 v108, v108
	v_rcp_f32_e32 v109, v109
	v_mul_f32_e32 v101, v101, v120
	v_mul_f32_e32 v97, v97, v120
	s_waitcnt vmcnt(0)
; __device__ __forceinline__ float sigmoid_f(float x) { return __builtin_amdgcn_rcpf(1.0f + __builtin_amdgcn_exp2f(-x * LOG2E)); }
; __device__ __forceinline__ u32x4 pack8(const f32x4 a, const f32x4 b) { u32x4 w; w.x = cvt_pk_bf16(a[0], a[1]); w.y = cvt_pk_bf16(a[2], a[3]); w.z = cvt_pk_bf16(b[0], b[1]); w.w = cvt_pk_bf16(b[2], b[3]); return w; }
; __device__ __forceinline__ void unpack8(const u32x4 w, f32x4& a, f32x4& b) { a = (f32x4){bf_lo(w.x), bf_hi(w.x), bf_lo(w.y), bf_hi(w.y)}; b = (f32x4){bf_lo(w.z), bf_hi(w.z), bf_lo(w.w), bf_hi(w.w)}; }
;     __device__ __forceinline__ void operator()(const Acc& acc, const Unit& u, int wr, int wc, int fr, int fq, const float (&sv8)[8]) const {
;     ...
;             for (int m = 0; m < 4; ++m) {
;                 const float rs = rsqrtf(sv8[ai * 4 + m] * (1.0f / DM) + EPS);
;                 f32x4 a0, a1, m0, m1; unpack8(ar[m], a0, a1); unpack8(mr[m], m0, m1);
;                 f32x4 o0, o1;
; #pragma unroll
;                 for (int j = 0; j < 4; ++j) { o0[j] = sigmoid_f(acc[ai][0][m][0][j] * rs) * a0[j] + sigmoid_f(acc[ai][1][m][0][j] * rs) * m0[j];
;                                               o1[j] = sigmoid_f(acc[ai][0][m][1][j] * rs) * a1[j] + sigmoid_f(acc[ai][1][m][1][j] * rs) * m1[j]; }
;                 *(u32x4*)(MRG + (size_t)(rowb + ai * 128 + m * 16) * 2048 + col0) = pack8(o0, o1);
	v_lshlrev_b32_e32 v116, 16, v144
	v_and_b32_e32 v117, 0xffff0000, v144
	v_mul_f32_e32 v101, 0xbfb8aa3b, v101
	v_mul_f32_e32 v97, 0xbfb8aa3b, v97
	v_pk_mul_f32 v[108:109], v[108:109], v[116:117]
	v_exp_f32_e32 v101, v101
	v_exp_f32_e32 v116, v97
	v_rcp_f32_e32 v104, v104
	v_rcp_f32_e32 v105, v105
	v_add_f32_e32 v97, 1.0, v101
	v_add_f32_e32 v101, 1.0, v116
	v_rcp_f32_e32 v100, v100
	v_rcp_f32_e32 v101, v101
	v_mul_f32_e32 v106, v106, v120
	v_rcp_f32_e32 v96, v96
	v_rcp_f32_e32 v97, v97
	v_mul_f32_e32 v106, 0xbfb8aa3b, v106
	v_mul_f32_e32 v102, v102, v120
	v_lshlrev_b32_e32 v114, 16, v148
	v_and_b32_e32 v115, 0xffff0000, v148
	v_exp_f32_e32 v106, v106
	v_mul_f32_e32 v102, 0xbfb8aa3b, v102
	v_pk_fma_f32 v[104:105], v[104:105], v[114:115], v[108:109]
	v_lshlrev_b32_e32 v114, 16, v146
	v_and_b32_e32 v115, 0xffff0000, v146
	v_exp_f32_e32 v102, v102
	v_mul_f32_e32 v98, v98, v120
	v_lshlrev_b32_e32 v108, 16, v150
	v_and_b32_e32 v109, 0xffff0000, v150
	v_pk_mul_f32 v[100:101], v[100:101], v[114:115]
	v_mul_f32_e32 v98, 0xbfb8aa3b, v98
	v_pk_fma_f32 v[100:101], v[96:97], v[108:109], v[100:101]
	v_exp_f32_e32 v108, v98
	v_add_f32_e32 v97, 1.0, v106
	v_rcp_f32_e32 v106, v97
	v_add_f32_e32 v97, 1.0, v102
	v_mul_f32_e32 v102, v111, v120
	v_mul_f32_e32 v102, 0xbfb8aa3b, v102
	v_rcp_f32_e32 v98, v97
	v_add_f32_e32 v97, 1.0, v108
	v_exp_f32_e32 v108, v102
	v_mul_f32_e32 v102, v107, v120
	v_mul_f32_e32 v102, 0xbfb8aa3b, v102
	v_exp_f32_e32 v107, v102
	v_mul_f32_e32 v110, v110, v120
	v_mul_f32_e32 v110, 0xbfb8aa3b, v110
	v_exp_f32_e32 v110, v110
	v_add_f32_e32 v107, 1.0, v107
	v_rcp_f32_e32 v107, v107
	v_mul_f32_e32 v103, v103, v120
	v_add_f32_e32 v96, 1.0, v110
	v_rcp_f32_e32 v102, v97
	v_add_f32_e32 v97, 1.0, v108
	v_mul_f32_e32 v103, 0xbfb8aa3b, v103
	v_mul_f32_e32 v99, v99, v120
	v_rcp_f32_e32 v96, v96
	v_rcp_f32_e32 v97, v97
	v_lshlrev_b32_e32 v110, 16, v145
	v_and_b32_e32 v111, 0xffff0000, v145
	v_exp_f32_e32 v103, v103
	v_mul_f32_e32 v99, 0xbfb8aa3b, v99
	v_pk_mul_f32 v[106:107], v[106:107], v[110:111]
	v_exp_f32_e32 v110, v99
	v_lshlrev_b32_e32 v108, 16, v149
	v_and_b32_e32 v109, 0xffff0000, v149
	v_pk_fma_f32 v[106:107], v[96:97], v[108:109], v[106:107]
	v_add_f32_e32 v96, 1.0, v103
	v_rcp_f32_e32 v99, v96
	v_add_f32_e32 v96, 1.0, v110
	v_rcp_f32_e32 v103, v96
	v_lshlrev_b32_e32 v108, 16, v147
	v_and_b32_e32 v109, 0xffff0000, v147
	v_lshlrev_b32_e32 v96, 16, v151
	v_and_b32_e32 v97, 0xffff0000, v151
	v_pk_mul_f32 v[102:103], v[102:103], v[108:109]
	s_nop 0
	v_pk_fma_f32 v[102:103], v[98:99], v[96:97], v[102:103]
	v_cvt_pk_bf16_f32 v98, v100, v101
	v_fmamk_f32 v100, v232, 0x3a000000, v226
	v_mul_f32_e32 v101, 0x4b800000, v100
	v_cmp_gt_f32_e32 vcc, s56, v100
	v_cvt_pk_bf16_f32 v99, v102, v103
	v_cvt_pk_bf16_f32 v96, v104, v105
	v_cndmask_b32_e32 v100, v100, v101, vcc
	v_rsq_f32_e32 v102, v100
	v_lshlrev_b64 v[100:101], 12, v[158:159]
	v_lshl_add_u64 v[100:101], s[12:13], 0, v[100:101]
	v_cvt_pk_bf16_f32 v97, v106, v107
	v_mul_f32_e32 v103, 0x45800000, v102
	v_cndmask_b32_e32 v102, v102, v103, vcc
	v_mul_f32_e32 v84, v84, v102
	v_mul_f32_e32 v80, v80, v102
	v_lshl_add_u64 v[100:101], v[100:101], 0, v[112:113]
	v_mul_f32_e32 v84, 0xbfb8aa3b, v84
	v_mul_f32_e32 v80, 0xbfb8aa3b, v80
	global_store_dwordx4 v[100:101], v[96:99], off
	v_exp_f32_e32 v84, v84
	v_mul_f32_e32 v92, v92, v102
	v_exp_f32_e32 v96, v80
	v_mul_f32_e32 v88, v88, v102
	v_mul_f32_e32 v93, v93, v102
	v_mul_f32_e32 v89, v89, v102
	v_mul_f32_e32 v92, 0xbfb8aa3b, v92
	v_mul_f32_e32 v88, 0xbfb8aa3b, v88
	v_mul_f32_e32 v93, 0xbfb8aa3b, v93
	v_mul_f32_e32 v89, 0xbfb8aa3b, v89
	v_exp_f32_e32 v92, v92
	v_exp_f32_e32 v103, v88
	v_add_f32_e32 v80, 1.0, v84
	v_add_f32_e32 v84, 1.0, v96
	v_exp_f32_e32 v93, v93
	v_exp_f32_e32 v96, v89
	v_add_f32_e32 v88, 1.0, v92
	v_add_f32_e32 v92, 1.0, v103
	v_add_f32_e32 v89, 1.0, v93
	v_add_f32_e32 v93, 1.0, v96
	v_rcp_f32_e32 v92, v92
	v_rcp_f32_e32 v93, v93
	v_mul_f32_e32 v85, v85, v102
	v_mul_f32_e32 v81, v81, v102
	v_lshlrev_b32_e32 v98, 16, v136
	v_and_b32_e32 v99, 0xffff0000, v136
	v_mul_f32_e32 v85, 0xbfb8aa3b, v85
	v_mul_f32_e32 v81, 0xbfb8aa3b, v81
	v_pk_mul_f32 v[92:93], v[92:93], v[98:99]
	v_exp_f32_e32 v85, v85
	v_exp_f32_e32 v98, v81
	v_rcp_f32_e32 v88, v88
	v_rcp_f32_e32 v89, v89
	v_add_f32_e32 v81, 1.0, v85
	v_add_f32_e32 v85, 1.0, v98
	v_rcp_f32_e32 v84, v84
	v_rcp_f32_e32 v85, v85
	v_mul_f32_e32 v90, v90, v102
	v_rcp_f32_e32 v80, v80
	v_rcp_f32_e32 v81, v81
	v_mul_f32_e32 v90, 0xbfb8aa3b, v90
	v_mul_f32_e32 v86, v86, v102
	v_lshlrev_b32_e32 v96, 16, v140
	v_and_b32_e32 v97, 0xffff0000, v140
	v_exp_f32_e32 v90, v90
	v_mul_f32_e32 v86, 0xbfb8aa3b, v86
	v_pk_fma_f32 v[88:89], v[88:89], v[96:97], v[92:93]
	v_lshlrev_b32_e32 v96, 16, v138
	v_and_b32_e32 v97, 0xffff0000, v138
	v_exp_f32_e32 v86, v86
	v_mul_f32_e32 v82, v82, v102
	v_lshlrev_b32_e32 v92, 16, v142
	v_and_b32_e32 v93, 0xffff0000, v142
	v_pk_mul_f32 v[84:85], v[84:85], v[96:97]
	v_mul_f32_e32 v82, 0xbfb8aa3b, v82
	v_pk_fma_f32 v[84:85], v[80:81], v[92:93], v[84:85]
	v_exp_f32_e32 v92, v82
	v_add_f32_e32 v81, 1.0, v90
	v_rcp_f32_e32 v90, v81
	v_add_f32_e32 v81, 1.0, v86
	v_mul_f32_e32 v86, v95, v102
	v_mul_f32_e32 v86, 0xbfb8aa3b, v86
	v_rcp_f32_e32 v82, v81
	v_add_f32_e32 v81, 1.0, v92
	v_exp_f32_e32 v92, v86
	v_mul_f32_e32 v86, v91, v102
	v_mul_f32_e32 v86, 0xbfb8aa3b, v86
	v_exp_f32_e32 v91, v86
	v_mul_f32_e32 v94, v94, v102
	v_mul_f32_e32 v94, 0xbfb8aa3b, v94
	v_exp_f32_e32 v94, v94
	v_add_f32_e32 v91, 1.0, v91
	v_rcp_f32_e32 v91, v91
	v_mul_f32_e32 v87, v87, v102
	v_add_f32_e32 v80, 1.0, v94
	v_rcp_f32_e32 v86, v81
	v_add_f32_e32 v81, 1.0, v92
	v_mul_f32_e32 v87, 0xbfb8aa3b, v87
; __device__ __forceinline__ float sigmoid_f(float x) { return __builtin_amdgcn_rcpf(1.0f + __builtin_amdgcn_exp2f(-x * LOG2E)); }
; __device__ __forceinline__ u32x4 pack8(const f32x4 a, const f32x4 b) { u32x4 w; w.x = cvt_pk_bf16(a[0], a[1]); w.y = cvt_pk_bf16(a[2], a[3]); w.z = cvt_pk_bf16(b[0], b[1]); w.w = cvt_pk_bf16(b[2], b[3]); return w; }
; __device__ __forceinline__ void unpack8(const u32x4 w, f32x4& a, f32x4& b) { a = (f32x4){bf_lo(w.x), bf_hi(w.x), bf_lo(w.y), bf_hi(w.y)}; b = (f32x4){bf_lo(w.z), bf_hi(w.z), bf_lo(w.w), bf_hi(w.w)}; }
;     __device__ __forceinline__ void operator()(const Acc& acc, const Unit& u, int wr, int wc, int fr, int fq, const float (&sv8)[8]) const {
;     ...
;             for (int m = 0; m < 4; ++m) { const size_t off = (size_t)(rowb + ai * 128 + m * 16) * 2048 + col0; ar[m] = *(const u32x4*)(MRG + off); mr[m] = *(const u32x4*)(MS + off); }
; #pragma unroll
;             for (int m = 0; m < 4; ++m) {
;                 const float rs = rsqrtf(sv8[ai * 4 + m] * (1.0f / DM) + EPS);
;                 f32x4 a0, a1, m0, m1; unpack8(ar[m], a0, a1); unpack8(mr[m], m0, m1);
;                 f32x4 o0, o1;
; #pragma unroll
;                 for (int j = 0; j < 4; ++j) { o0[j] = sigmoid_f(acc[ai][0][m][0][j] * rs) * a0[j] + sigmoid_f(acc[ai][1][m][0][j] * rs) * m0[j];
;                                               o1[j] = sigmoid_f(acc[ai][0][m][1][j] * rs) * a1[j] + sigmoid_f(acc[ai][1][m][1][j] * rs) * m1[j]; }
;                 *(u32x4*)(MRG + (size_t)(rowb + ai * 128 + m * 16) * 2048 + col0) = pack8(o0, o1);
	v_mul_f32_e32 v83, v83, v102
	v_rcp_f32_e32 v80, v80
	v_rcp_f32_e32 v81, v81
	v_lshlrev_b32_e32 v94, 16, v137
	v_and_b32_e32 v95, 0xffff0000, v137
	v_exp_f32_e32 v87, v87
	v_mul_f32_e32 v83, 0xbfb8aa3b, v83
	v_pk_mul_f32 v[90:91], v[90:91], v[94:95]
	v_exp_f32_e32 v94, v83
	v_lshlrev_b32_e32 v92, 16, v141
	v_and_b32_e32 v93, 0xffff0000, v141
	v_pk_fma_f32 v[90:91], v[80:81], v[92:93], v[90:91]
	v_add_f32_e32 v80, 1.0, v87
	v_rcp_f32_e32 v83, v80
	v_add_f32_e32 v80, 1.0, v94
	v_rcp_f32_e32 v87, v80
	v_lshlrev_b32_e32 v92, 16, v139
	v_and_b32_e32 v93, 0xffff0000, v139
	v_lshlrev_b32_e32 v80, 16, v143
	v_and_b32_e32 v81, 0xffff0000, v143
	v_pk_mul_f32 v[86:87], v[86:87], v[92:93]
	v_add_u32_e32 v102, 0x80, v208
	v_pk_fma_f32 v[86:87], v[82:83], v[80:81], v[86:87]
	v_cvt_pk_bf16_f32 v82, v84, v85
	v_fmamk_f32 v84, v231, 0x3a000000, v226
	v_mul_f32_e32 v85, 0x4b800000, v84
	v_cmp_gt_f32_e32 vcc, s56, v84
	v_cvt_pk_bf16_f32 v83, v86, v87
	v_cvt_pk_bf16_f32 v80, v88, v89
	v_cndmask_b32_e32 v84, v84, v85, vcc
	v_rsq_f32_e32 v86, v84
	v_lshlrev_b64 v[84:85], 12, v[156:157]
	v_lshl_add_u64 v[84:85], s[12:13], 0, v[84:85]
	v_cvt_pk_bf16_f32 v81, v90, v91
	v_mul_f32_e32 v87, 0x45800000, v86
	v_cndmask_b32_e32 v86, v86, v87, vcc
	v_mul_f32_e32 v68, v68, v86
	v_mul_f32_e32 v64, v64, v86
	v_lshl_add_u64 v[84:85], v[84:85], 0, v[112:113]
	v_mul_f32_e32 v68, 0xbfb8aa3b, v68
	v_mul_f32_e32 v64, 0xbfb8aa3b, v64
	global_store_dwordx4 v[84:85], v[80:83], off
	v_exp_f32_e32 v68, v68
	v_mul_f32_e32 v76, v76, v86
	v_exp_f32_e32 v80, v64
	v_mul_f32_e32 v72, v72, v86
	v_mul_f32_e32 v77, v77, v86
	v_mul_f32_e32 v73, v73, v86
	v_mul_f32_e32 v76, 0xbfb8aa3b, v76
	v_mul_f32_e32 v72, 0xbfb8aa3b, v72
	v_mul_f32_e32 v77, 0xbfb8aa3b, v77
	v_mul_f32_e32 v73, 0xbfb8aa3b, v73
	v_exp_f32_e32 v76, v76
	v_exp_f32_e32 v87, v72
	v_add_f32_e32 v64, 1.0, v68
	v_add_f32_e32 v68, 1.0, v80
	v_exp_f32_e32 v77, v77
	v_exp_f32_e32 v80, v73
	v_add_f32_e32 v72, 1.0, v76
	v_add_f32_e32 v76, 1.0, v87
	v_add_f32_e32 v73, 1.0, v77
	v_add_f32_e32 v77, 1.0, v80
	v_rcp_f32_e32 v76, v76
	v_rcp_f32_e32 v77, v77
	v_mul_f32_e32 v69, v69, v86
	v_mul_f32_e32 v65, v65, v86
	v_lshlrev_b32_e32 v82, 16, v128
	v_and_b32_e32 v83, 0xffff0000, v128
	v_mul_f32_e32 v69, 0xbfb8aa3b, v69
	v_mul_f32_e32 v65, 0xbfb8aa3b, v65
	v_pk_mul_f32 v[76:77], v[76:77], v[82:83]
	v_exp_f32_e32 v69, v69
	v_exp_f32_e32 v82, v65
	v_rcp_f32_e32 v72, v72
	v_rcp_f32_e32 v73, v73
	v_add_f32_e32 v65, 1.0, v69
	v_add_f32_e32 v69, 1.0, v82
	v_rcp_f32_e32 v68, v68
	v_rcp_f32_e32 v69, v69
	v_mul_f32_e32 v74, v74, v86
	v_rcp_f32_e32 v64, v64
	v_rcp_f32_e32 v65, v65
	v_mul_f32_e32 v74, 0xbfb8aa3b, v74
	v_mul_f32_e32 v70, v70, v86
	v_lshlrev_b32_e32 v80, 16, v132
	v_and_b32_e32 v81, 0xffff0000, v132
	v_exp_f32_e32 v74, v74
	v_mul_f32_e32 v70, 0xbfb8aa3b, v70
	v_pk_fma_f32 v[72:73], v[72:73], v[80:81], v[76:77]
	v_lshlrev_b32_e32 v80, 16, v130
	v_and_b32_e32 v81, 0xffff0000, v130
	v_exp_f32_e32 v70, v70
	v_mul_f32_e32 v66, v66, v86
	v_lshlrev_b32_e32 v76, 16, v134
	v_and_b32_e32 v77, 0xffff0000, v134
	v_pk_mul_f32 v[68:69], v[68:69], v[80:81]
	v_mul_f32_e32 v66, 0xbfb8aa3b, v66
	v_pk_fma_f32 v[68:69], v[64:65], v[76:77], v[68:69]
	v_exp_f32_e32 v76, v66
	v_add_f32_e32 v65, 1.0, v74
	v_rcp_f32_e32 v74, v65
	v_add_f32_e32 v65, 1.0, v70
	v_mul_f32_e32 v70, v79, v86
	v_mul_f32_e32 v70, 0xbfb8aa3b, v70
	v_rcp_f32_e32 v66, v65
	v_add_f32_e32 v65, 1.0, v76
	v_exp_f32_e32 v76, v70
	v_mul_f32_e32 v70, v75, v86
	v_mul_f32_e32 v70, 0xbfb8aa3b, v70
	v_exp_f32_e32 v75, v70
	v_mul_f32_e32 v78, v78, v86
	v_mul_f32_e32 v78, 0xbfb8aa3b, v78
	v_exp_f32_e32 v78, v78
	v_add_f32_e32 v75, 1.0, v75
	v_rcp_f32_e32 v75, v75
	v_mul_f32_e32 v71, v71, v86
	v_add_f32_e32 v64, 1.0, v78
	v_rcp_f32_e32 v70, v65
	v_add_f32_e32 v65, 1.0, v76
	v_mul_f32_e32 v71, 0xbfb8aa3b, v71
	v_mul_f32_e32 v67, v67, v86
	v_rcp_f32_e32 v64, v64
	v_rcp_f32_e32 v65, v65
	v_lshlrev_b32_e32 v78, 16, v129
	v_and_b32_e32 v79, 0xffff0000, v129
	v_exp_f32_e32 v71, v71
	v_mul_f32_e32 v67, 0xbfb8aa3b, v67
	v_pk_mul_f32 v[74:75], v[74:75], v[78:79]
	v_exp_f32_e32 v78, v67
	v_lshlrev_b32_e32 v76, 16, v133
	v_and_b32_e32 v77, 0xffff0000, v133
	v_pk_fma_f32 v[74:75], v[64:65], v[76:77], v[74:75]
	v_add_f32_e32 v64, 1.0, v71
	v_rcp_f32_e32 v67, v64
	v_add_f32_e32 v64, 1.0, v78
	v_rcp_f32_e32 v71, v64
	v_lshlrev_b32_e32 v76, 16, v131
	v_and_b32_e32 v77, 0xffff0000, v131
	v_lshlrev_b32_e32 v64, 16, v135
	v_and_b32_e32 v65, 0xffff0000, v135
	v_pk_mul_f32 v[70:71], v[70:71], v[76:77]
	v_ashrrev_i32_e32 v103, 31, v102
	v_pk_fma_f32 v[70:71], v[66:67], v[64:65], v[70:71]
	v_cvt_pk_bf16_f32 v66, v68, v69
	v_lshlrev_b64 v[68:69], 12, v[154:155]
	v_lshl_add_u64 v[68:69], s[12:13], 0, v[68:69]
	v_cvt_pk_bf16_f32 v64, v72, v73
	v_cvt_pk_bf16_f32 v65, v74, v75
	v_cvt_pk_bf16_f32 v67, v70, v71
	v_lshl_add_u64 v[68:69], v[68:69], 0, v[112:113]
	global_store_dwordx4 v[68:69], v[64:67], off
	v_add_u32_e32 v92, 0x90, v208
	v_ashrrev_i32_e32 v93, 31, v92
	v_lshlrev_b64 v[64:65], 11, v[102:103]
	v_lshl_add_u64 v[64:65], v[64:65], 0, v[152:153]
	v_lshlrev_b64 v[64:65], 1, v[64:65]
	v_lshl_add_u64 v[66:67], s[12:13], 0, v[64:65]
	global_load_dwordx4 v[94:97], v[66:67], off
	v_lshl_add_u64 v[64:65], s[14:15], 0, v[64:65]
	global_load_dwordx4 v[98:101], v[64:65], off
	v_lshlrev_b64 v[64:65], 11, v[92:93]
	v_lshl_add_u64 v[64:65], v[64:65], 0, v[152:153]
	v_lshlrev_b64 v[64:65], 1, v[64:65]
	v_add_u32_e32 v90, 0xa0, v208
	v_lshl_add_u64 v[66:67], s[12:13], 0, v[64:65]
	v_lshl_add_u64 v[64:65], s[14:15], 0, v[64:65]
	v_ashrrev_i32_e32 v91, 31, v90
	global_load_dwordx4 v[84:87], v[66:67], off
	global_load_dwordx4 v[80:83], v[64:65], off
; __device__ __forceinline__ float sigmoid_f(float x) { return __builtin_amdgcn_rcpf(1.0f + __builtin_amdgcn_exp2f(-x * LOG2E)); }
; __device__ __forceinline__ u32x4 pack8(const f32x4 a, const f32x4 b) { u32x4 w; w.x = cvt_pk_bf16(a[0], a[1]); w.y = cvt_pk_bf16(a[2], a[3]); w.z = cvt_pk_bf16(b[0], b[1]); w.w = cvt_pk_bf16(b[2], b[3]); return w; }
; __device__ __forceinline__ void unpack8(const u32x4 w, f32x4& a, f32x4& b) { a = (f32x4){bf_lo(w.x), bf_hi(w.x), bf_lo(w.y), bf_hi(w.y)}; b = (f32x4){bf_lo(w.z), bf_hi(w.z), bf_lo(w.w), bf_hi(w.w)}; }
;     __device__ __forceinline__ void operator()(const Acc& acc, const Unit& u, int wr, int wc, int fr, int fq, const float (&sv8)[8]) const {
;     ...
;         for (int ai = 0; ai < 2; ++ai) {
;             u32x4 ar[4], mr[4];
; #pragma unroll
;             for (int m = 0; m < 4; ++m) { const size_t off = (size_t)(rowb + ai * 128 + m * 16) * 2048 + col0; ar[m] = *(const u32x4*)(MRG + off); mr[m] = *(const u32x4*)(MS + off); }
; #pragma unroll
;             for (int m = 0; m < 4; ++m) {
;                 const float rs = rsqrtf(sv8[ai * 4 + m] * (1.0f / DM) + EPS);
;                 f32x4 a0, a1, m0, m1; unpack8(ar[m], a0, a1); unpack8(mr[m], m0, m1);
;                 f32x4 o0, o1;
; #pragma unroll
;                 for (int j = 0; j < 4; ++j) { o0[j] = sigmoid_f(acc[ai][0][m][0][j] * rs) * a0[j] + sigmoid_f(acc[ai][1][m][0][j] * rs) * m0[j];
;                                               o1[j] = sigmoid_f(acc[ai][0][m][1][j] * rs) * a1[j] + sigmoid_f(acc[ai][1][m][1][j] * rs) * m1[j]; }
;                 *(u32x4*)(MRG + (size_t)(rowb + ai * 128 + m * 16) * 2048 + col0) = pack8(o0, o1);
	v_lshlrev_b64 v[64:65], 11, v[90:91]
	v_lshl_add_u64 v[64:65], v[64:65], 0, v[152:153]
	v_lshlrev_b64 v[64:65], 1, v[64:65]
	v_lshl_add_u64 v[66:67], s[12:13], 0, v[64:65]
	v_lshl_add_u64 v[64:65], s[14:15], 0, v[64:65]
	global_load_dwordx4 v[76:79], v[66:67], off
	global_load_dwordx4 v[72:75], v[64:65], off
	v_fmamk_f32 v66, v230, 0x3a000000, v226
	v_mul_f32_e32 v67, 0x4b800000, v66
	v_cmp_gt_f32_e32 vcc, s56, v66
	v_add_u32_e32 v88, 0xb0, v208
	v_ashrrev_i32_e32 v89, 31, v88
	v_cndmask_b32_e32 v66, v66, v67, vcc
	v_rsq_f32_e32 v68, v66
	v_lshlrev_b64 v[64:65], 11, v[88:89]
	v_lshl_add_u64 v[64:65], v[64:65], 0, v[152:153]
	v_lshlrev_b64 v[64:65], 1, v[64:65]
	v_mul_f32_e32 v69, 0x45800000, v68
	v_cndmask_b32_e32 v108, v68, v69, vcc
	v_mul_f32_e32 v60, v60, v108
	v_mul_f32_e32 v56, v56, v108
	v_mul_f32_e32 v60, 0xbfb8aa3b, v60
	v_mul_f32_e32 v56, 0xbfb8aa3b, v56
	v_exp_f32_e32 v60, v60
	v_exp_f32_e32 v104, v56
	v_mul_f32_e32 v52, v52, v108
	v_mul_f32_e32 v48, v48, v108
	v_mul_f32_e32 v52, 0xbfb8aa3b, v52
	v_mul_f32_e32 v48, 0xbfb8aa3b, v48
	v_add_f32_e32 v56, 1.0, v60
	v_add_f32_e32 v60, 1.0, v104
	v_exp_f32_e32 v52, v52
	v_exp_f32_e32 v104, v48
	v_mul_f32_e32 v61, v61, v108
	v_mul_f32_e32 v57, v57, v108
	v_mul_f32_e32 v61, 0xbfb8aa3b, v61
	v_mul_f32_e32 v57, 0xbfb8aa3b, v57
	v_add_f32_e32 v48, 1.0, v52
	v_add_f32_e32 v52, 1.0, v104
	v_exp_f32_e32 v61, v61
	v_exp_f32_e32 v104, v57
	v_mul_f32_e32 v53, v53, v108
	v_mul_f32_e32 v49, v49, v108
	v_mul_f32_e32 v53, 0xbfb8aa3b, v53
	v_mul_f32_e32 v49, 0xbfb8aa3b, v49
	v_add_f32_e32 v57, 1.0, v61
	v_add_f32_e32 v61, 1.0, v104
	v_exp_f32_e32 v53, v53
	v_rcp_f32_e32 v60, v60
	v_rcp_f32_e32 v61, v61
	v_rcp_f32_e32 v56, v56
	v_rcp_f32_e32 v57, v57
	v_rcp_f32_e32 v52, v52
	v_mul_f32_e32 v58, v58, v108
	v_rcp_f32_e32 v48, v48
	v_mul_f32_e32 v58, 0xbfb8aa3b, v58
	v_mul_f32_e32 v54, v54, v108
	v_exp_f32_e32 v58, v58
	v_mul_f32_e32 v54, 0xbfb8aa3b, v54
	v_exp_f32_e32 v54, v54
	v_mul_f32_e32 v50, v50, v108
	v_mul_f32_e32 v50, 0xbfb8aa3b, v50
	v_mul_f32_e32 v62, v62, v108
	v_mul_f32_e32 v62, 0xbfb8aa3b, v62
	v_exp_f32_e32 v62, v62
	v_mul_f32_e32 v55, v55, v108
	v_mul_f32_e32 v55, 0xbfb8aa3b, v55
	v_mul_f32_e32 v51, v51, v108
	v_exp_f32_e32 v55, v55
	v_mul_f32_e32 v51, 0xbfb8aa3b, v51
	s_waitcnt vmcnt(0)
	v_lshlrev_b32_e32 v104, 16, v94
	v_and_b32_e32 v105, 0xffff0000, v94
	v_exp_f32_e32 v94, v49
	v_add_f32_e32 v49, 1.0, v53
	v_lshlrev_b32_e32 v106, 16, v98
	v_and_b32_e32 v107, 0xffff0000, v98
	v_add_f32_e32 v53, 1.0, v94
	v_rcp_f32_e32 v53, v53
	v_rcp_f32_e32 v49, v49
	v_pk_mul_f32 v[60:61], v[60:61], v[106:107]
	v_lshl_add_u64 v[66:67], s[12:13], 0, v[64:65]
	v_pk_fma_f32 v[56:57], v[56:57], v[104:105], v[60:61]
	v_lshlrev_b32_e32 v104, 16, v100
	v_and_b32_e32 v105, 0xffff0000, v100
	v_lshlrev_b32_e32 v60, 16, v96
	v_and_b32_e32 v61, 0xffff0000, v96
	v_pk_mul_f32 v[52:53], v[52:53], v[104:105]
	v_lshl_add_u64 v[64:65], s[14:15], 0, v[64:65]
	v_pk_fma_f32 v[52:53], v[48:49], v[60:61], v[52:53]
	v_exp_f32_e32 v60, v50
	v_add_f32_e32 v49, 1.0, v58
	v_rcp_f32_e32 v58, v49
	v_add_f32_e32 v49, 1.0, v54
	v_mul_f32_e32 v54, v63, v108
	v_mul_f32_e32 v54, 0xbfb8aa3b, v54
	v_rcp_f32_e32 v50, v49
	v_add_f32_e32 v49, 1.0, v60
	v_exp_f32_e32 v60, v54
	v_mul_f32_e32 v54, v59, v108
	v_mul_f32_e32 v54, 0xbfb8aa3b, v54
	v_exp_f32_e32 v59, v54
	v_add_f32_e32 v48, 1.0, v62
	v_rcp_f32_e32 v54, v49
	v_add_f32_e32 v49, 1.0, v60
	v_add_f32_e32 v59, 1.0, v59
	v_rcp_f32_e32 v59, v59
	v_rcp_f32_e32 v48, v48
	v_rcp_f32_e32 v49, v49
	v_lshlrev_b32_e32 v62, 16, v99
	v_and_b32_e32 v63, 0xffff0000, v99
	v_pk_mul_f32 v[58:59], v[58:59], v[62:63]
	v_exp_f32_e32 v62, v51
	v_lshlrev_b32_e32 v60, 16, v95
	v_and_b32_e32 v61, 0xffff0000, v95
	v_pk_fma_f32 v[58:59], v[48:49], v[60:61], v[58:59]
	v_add_f32_e32 v48, 1.0, v55
	v_rcp_f32_e32 v51, v48
	v_add_f32_e32 v48, 1.0, v62
	v_rcp_f32_e32 v55, v48
	v_lshlrev_b32_e32 v60, 16, v101
	v_and_b32_e32 v61, 0xffff0000, v101
	v_lshlrev_b32_e32 v48, 16, v97
	v_and_b32_e32 v49, 0xffff0000, v97
	v_pk_mul_f32 v[54:55], v[54:55], v[60:61]
	global_load_dwordx4 v[68:71], v[66:67], off
	s_nop 0
	global_load_dwordx4 v[64:67], v[64:65], off
	v_pk_fma_f32 v[54:55], v[50:51], v[48:49], v[54:55]
	v_cvt_pk_bf16_f32 v50, v52, v53
	v_fmamk_f32 v52, v229, 0x3a000000, v226
	v_mul_f32_e32 v53, 0x4b800000, v52
	v_cmp_gt_f32_e32 vcc, s56, v52
	v_cvt_pk_bf16_f32 v51, v54, v55
	v_cvt_pk_bf16_f32 v48, v56, v57
	v_cndmask_b32_e32 v52, v52, v53, vcc
	v_rsq_f32_e32 v54, v52
	v_lshlrev_b64 v[52:53], 12, v[102:103]
	v_lshl_add_u64 v[52:53], s[12:13], 0, v[52:53]
	v_cvt_pk_bf16_f32 v49, v58, v59
	v_mul_f32_e32 v55, 0x45800000, v54
	v_cndmask_b32_e32 v54, v54, v55, vcc
	v_mul_f32_e32 v36, v36, v54
	v_mul_f32_e32 v32, v32, v54
	v_lshl_add_u64 v[52:53], v[52:53], 0, v[112:113]
	v_mul_f32_e32 v36, 0xbfb8aa3b, v36
	v_mul_f32_e32 v32, 0xbfb8aa3b, v32
	global_store_dwordx4 v[52:53], v[48:51], off
	v_exp_f32_e32 v36, v36
	v_mul_f32_e32 v44, v44, v54
	v_exp_f32_e32 v48, v32
	v_mul_f32_e32 v40, v40, v54
	v_mul_f32_e32 v45, v45, v54
	v_mul_f32_e32 v41, v41, v54
	v_mul_f32_e32 v44, 0xbfb8aa3b, v44
	v_mul_f32_e32 v40, 0xbfb8aa3b, v40
	v_mul_f32_e32 v45, 0xbfb8aa3b, v45
	v_mul_f32_e32 v41, 0xbfb8aa3b, v41
	v_exp_f32_e32 v44, v44
	v_exp_f32_e32 v55, v40
	v_add_f32_e32 v32, 1.0, v36
	v_add_f32_e32 v36, 1.0, v48
	v_exp_f32_e32 v45, v45
	v_exp_f32_e32 v48, v41
	v_add_f32_e32 v40, 1.0, v44
	v_add_f32_e32 v44, 1.0, v55
	v_add_f32_e32 v41, 1.0, v45
	v_add_f32_e32 v45, 1.0, v48
	v_rcp_f32_e32 v44, v44
	v_rcp_f32_e32 v45, v45
	v_mul_f32_e32 v37, v37, v54
	v_mul_f32_e32 v33, v33, v54
	v_lshlrev_b32_e32 v50, 16, v80
	v_and_b32_e32 v51, 0xffff0000, v80
; __device__ __forceinline__ float sigmoid_f(float x) { return __builtin_amdgcn_rcpf(1.0f + __builtin_amdgcn_exp2f(-x * LOG2E)); }
; __device__ __forceinline__ u32x4 pack8(const f32x4 a, const f32x4 b) { u32x4 w; w.x = cvt_pk_bf16(a[0], a[1]); w.y = cvt_pk_bf16(a[2], a[3]); w.z = cvt_pk_bf16(b[0], b[1]); w.w = cvt_pk_bf16(b[2], b[3]); return w; }
; __device__ __forceinline__ void unpack8(const u32x4 w, f32x4& a, f32x4& b) { a = (f32x4){bf_lo(w.x), bf_hi(w.x), bf_lo(w.y), bf_hi(w.y)}; b = (f32x4){bf_lo(w.z), bf_hi(w.z), bf_lo(w.w), bf_hi(w.w)}; }
;     __device__ __forceinline__ void operator()(const Acc& acc, const Unit& u, int wr, int wc, int fr, int fq, const float (&sv8)[8]) const {
;     ...
;             for (int m = 0; m < 4; ++m) {
;                 const float rs = rsqrtf(sv8[ai * 4 + m] * (1.0f / DM) + EPS);
;                 f32x4 a0, a1, m0, m1; unpack8(ar[m], a0, a1); unpack8(mr[m], m0, m1);
;                 f32x4 o0, o1;
; #pragma unroll
;                 for (int j = 0; j < 4; ++j) { o0[j] = sigmoid_f(acc[ai][0][m][0][j] * rs) * a0[j] + sigmoid_f(acc[ai][1][m][0][j] * rs) * m0[j];
;                                               o1[j] = sigmoid_f(acc[ai][0][m][1][j] * rs) * a1[j] + sigmoid_f(acc[ai][1][m][1][j] * rs) * m1[j]; }
;                 *(u32x4*)(MRG + (size_t)(rowb + ai * 128 + m * 16) * 2048 + col0) = pack8(o0, o1);
	v_mul_f32_e32 v37, 0xbfb8aa3b, v37
	v_mul_f32_e32 v33, 0xbfb8aa3b, v33
	v_pk_mul_f32 v[44:45], v[44:45], v[50:51]
	v_exp_f32_e32 v37, v37
	v_exp_f32_e32 v50, v33
	v_rcp_f32_e32 v40, v40
	v_rcp_f32_e32 v41, v41
	v_add_f32_e32 v33, 1.0, v37
	v_add_f32_e32 v37, 1.0, v50
	v_rcp_f32_e32 v36, v36
	v_rcp_f32_e32 v37, v37
	v_mul_f32_e32 v42, v42, v54
	v_rcp_f32_e32 v32, v32
	v_rcp_f32_e32 v33, v33
	v_mul_f32_e32 v42, 0xbfb8aa3b, v42
	v_mul_f32_e32 v38, v38, v54
	v_lshlrev_b32_e32 v48, 16, v84
	v_and_b32_e32 v49, 0xffff0000, v84
	v_exp_f32_e32 v42, v42
	v_mul_f32_e32 v38, 0xbfb8aa3b, v38
	v_pk_fma_f32 v[40:41], v[40:41], v[48:49], v[44:45]
	v_lshlrev_b32_e32 v48, 16, v82
	v_and_b32_e32 v49, 0xffff0000, v82
	v_exp_f32_e32 v38, v38
	v_mul_f32_e32 v34, v34, v54
	v_lshlrev_b32_e32 v44, 16, v86
	v_and_b32_e32 v45, 0xffff0000, v86
	v_pk_mul_f32 v[36:37], v[36:37], v[48:49]
	v_mul_f32_e32 v34, 0xbfb8aa3b, v34
	v_pk_fma_f32 v[36:37], v[32:33], v[44:45], v[36:37]
	v_exp_f32_e32 v44, v34
	v_add_f32_e32 v33, 1.0, v42
	v_rcp_f32_e32 v42, v33
	v_add_f32_e32 v33, 1.0, v38
	v_mul_f32_e32 v38, v47, v54
	v_mul_f32_e32 v38, 0xbfb8aa3b, v38
	v_rcp_f32_e32 v34, v33
	v_add_f32_e32 v33, 1.0, v44
	v_exp_f32_e32 v44, v38
	v_mul_f32_e32 v38, v43, v54
	v_mul_f32_e32 v38, 0xbfb8aa3b, v38
	v_exp_f32_e32 v43, v38
	v_mul_f32_e32 v46, v46, v54
	v_mul_f32_e32 v46, 0xbfb8aa3b, v46
	v_exp_f32_e32 v46, v46
	v_add_f32_e32 v43, 1.0, v43
	v_rcp_f32_e32 v43, v43
	v_mul_f32_e32 v39, v39, v54
	v_add_f32_e32 v32, 1.0, v46
	v_rcp_f32_e32 v38, v33
	v_add_f32_e32 v33, 1.0, v44
	v_mul_f32_e32 v39, 0xbfb8aa3b, v39
	v_mul_f32_e32 v35, v35, v54
	v_rcp_f32_e32 v32, v32
	v_rcp_f32_e32 v33, v33
	v_lshlrev_b32_e32 v46, 16, v81
	v_and_b32_e32 v47, 0xffff0000, v81
	v_exp_f32_e32 v39, v39
	v_mul_f32_e32 v35, 0xbfb8aa3b, v35
	v_pk_mul_f32 v[42:43], v[42:43], v[46:47]
	v_exp_f32_e32 v46, v35
	v_lshlrev_b32_e32 v44, 16, v85
	v_and_b32_e32 v45, 0xffff0000, v85
	v_pk_fma_f32 v[42:43], v[32:33], v[44:45], v[42:43]
	v_add_f32_e32 v32, 1.0, v39
	v_rcp_f32_e32 v35, v32
	v_add_f32_e32 v32, 1.0, v46
	v_rcp_f32_e32 v39, v32
	v_lshlrev_b32_e32 v44, 16, v83
	v_and_b32_e32 v45, 0xffff0000, v83
	v_lshlrev_b32_e32 v32, 16, v87
	v_and_b32_e32 v33, 0xffff0000, v87
	v_pk_mul_f32 v[38:39], v[38:39], v[44:45]
	s_nop 0
	v_pk_fma_f32 v[38:39], v[34:35], v[32:33], v[38:39]
	v_cvt_pk_bf16_f32 v34, v36, v37
	v_fmamk_f32 v36, v228, 0x3a000000, v226
	v_mul_f32_e32 v37, 0x4b800000, v36
	v_cmp_gt_f32_e32 vcc, s56, v36
	v_cvt_pk_bf16_f32 v35, v38, v39
	v_cvt_pk_bf16_f32 v32, v40, v41
	v_cndmask_b32_e32 v36, v36, v37, vcc
	v_rsq_f32_e32 v38, v36
	v_lshlrev_b64 v[36:37], 12, v[92:93]
	v_lshl_add_u64 v[36:37], s[12:13], 0, v[36:37]
	v_cvt_pk_bf16_f32 v33, v42, v43
	v_mul_f32_e32 v39, 0x45800000, v38
	v_cndmask_b32_e32 v38, v38, v39, vcc
	v_mul_f32_e32 v20, v20, v38
	v_mul_f32_e32 v16, v16, v38
	v_lshl_add_u64 v[36:37], v[36:37], 0, v[112:113]
	v_mul_f32_e32 v20, 0xbfb8aa3b, v20
	v_mul_f32_e32 v16, 0xbfb8aa3b, v16
	global_store_dwordx4 v[36:37], v[32:35], off
	v_exp_f32_e32 v20, v20
	v_mul_f32_e32 v28, v28, v38
	v_exp_f32_e32 v32, v16
	v_mul_f32_e32 v24, v24, v38
	v_mul_f32_e32 v29, v29, v38
	v_mul_f32_e32 v25, v25, v38
	v_mul_f32_e32 v28, 0xbfb8aa3b, v28
	v_mul_f32_e32 v24, 0xbfb8aa3b, v24
	v_mul_f32_e32 v29, 0xbfb8aa3b, v29
	v_mul_f32_e32 v25, 0xbfb8aa3b, v25
	v_exp_f32_e32 v28, v28
	v_exp_f32_e32 v39, v24
	v_add_f32_e32 v16, 1.0, v20
	v_add_f32_e32 v20, 1.0, v32
	v_exp_f32_e32 v29, v29
	v_exp_f32_e32 v32, v25
	v_add_f32_e32 v24, 1.0, v28
	v_add_f32_e32 v28, 1.0, v39
	v_add_f32_e32 v25, 1.0, v29
	v_add_f32_e32 v29, 1.0, v32
	v_rcp_f32_e32 v28, v28
	v_rcp_f32_e32 v29, v29
	v_mul_f32_e32 v21, v21, v38
	v_mul_f32_e32 v17, v17, v38
	v_lshlrev_b32_e32 v34, 16, v72
	v_and_b32_e32 v35, 0xffff0000, v72
	v_mul_f32_e32 v21, 0xbfb8aa3b, v21
	v_mul_f32_e32 v17, 0xbfb8aa3b, v17
	v_pk_mul_f32 v[28:29], v[28:29], v[34:35]
	v_exp_f32_e32 v21, v21
	v_exp_f32_e32 v34, v17
	v_rcp_f32_e32 v24, v24
	v_rcp_f32_e32 v25, v25
	v_add_f32_e32 v17, 1.0, v21
	v_add_f32_e32 v21, 1.0, v34
	v_rcp_f32_e32 v20, v20
	v_rcp_f32_e32 v21, v21
	v_mul_f32_e32 v26, v26, v38
	v_rcp_f32_e32 v16, v16
	v_rcp_f32_e32 v17, v17
	v_mul_f32_e32 v26, 0xbfb8aa3b, v26
	v_mul_f32_e32 v22, v22, v38
	v_lshlrev_b32_e32 v32, 16, v76
	v_and_b32_e32 v33, 0xffff0000, v76
	v_exp_f32_e32 v26, v26
	v_mul_f32_e32 v22, 0xbfb8aa3b, v22
	v_pk_fma_f32 v[24:25], v[24:25], v[32:33], v[28:29]
	v_lshlrev_b32_e32 v32, 16, v74
	v_and_b32_e32 v33, 0xffff0000, v74
	v_exp_f32_e32 v22, v22
	v_mul_f32_e32 v18, v18, v38
	v_lshlrev_b32_e32 v28, 16, v78
	v_and_b32_e32 v29, 0xffff0000, v78
	v_pk_mul_f32 v[20:21], v[20:21], v[32:33]
	v_mul_f32_e32 v18, 0xbfb8aa3b, v18
	v_pk_fma_f32 v[20:21], v[16:17], v[28:29], v[20:21]
	v_exp_f32_e32 v28, v18
	v_add_f32_e32 v17, 1.0, v26
	v_rcp_f32_e32 v26, v17
	v_add_f32_e32 v17, 1.0, v22
	v_mul_f32_e32 v22, v31, v38
	v_mul_f32_e32 v22, 0xbfb8aa3b, v22
	v_rcp_f32_e32 v18, v17
	v_add_f32_e32 v17, 1.0, v28
	v_exp_f32_e32 v28, v22
	v_mul_f32_e32 v22, v27, v38
	v_mul_f32_e32 v22, 0xbfb8aa3b, v22
	v_exp_f32_e32 v27, v22
	v_mul_f32_e32 v30, v30, v38
; __device__ __forceinline__ float sigmoid_f(float x) { return __builtin_amdgcn_rcpf(1.0f + __builtin_amdgcn_exp2f(-x * LOG2E)); }
; __device__ __forceinline__ u32x4 pack8(const f32x4 a, const f32x4 b) { u32x4 w; w.x = cvt_pk_bf16(a[0], a[1]); w.y = cvt_pk_bf16(a[2], a[3]); w.z = cvt_pk_bf16(b[0], b[1]); w.w = cvt_pk_bf16(b[2], b[3]); return w; }
; __device__ __forceinline__ void unpack8(const u32x4 w, f32x4& a, f32x4& b) { a = (f32x4){bf_lo(w.x), bf_hi(w.x), bf_lo(w.y), bf_hi(w.y)}; b = (f32x4){bf_lo(w.z), bf_hi(w.z), bf_lo(w.w), bf_hi(w.w)}; }
; #define PG8_BAR __builtin_amdgcn_s_barrier()
;     ...
;         if (!has_next) break;
; #pragma unroll
;         for (int a = 0; a < 2; ++a)
; #pragma unroll
;             for (int b = 0; b < 2; ++b)
; #pragma unroll
;                 for (int m = 0; m < 4; ++m)
; #pragma unroll
;                     for (int n = 0; n < 2; ++n) acc[a][b][m][n] = (f32x4){0.f, 0.f, 0.f, 0.f};
;         cur = nxt; cA = nA; cB = nB; ++ui;
;         if constexpr (ALIGN_EPI) { if (wr == 1) PG8_BAR; }
;     __device__ __forceinline__ void operator()(const Acc& acc, const Unit& u, int wr, int wc, int fr, int fq, const float (&sv8)[8]) const {
;     ...
;             for (int m = 0; m < 4; ++m) {
;                 const float rs = rsqrtf(sv8[ai * 4 + m] * (1.0f / DM) + EPS);
;                 f32x4 a0, a1, m0, m1; unpack8(ar[m], a0, a1); unpack8(mr[m], m0, m1);
;                 f32x4 o0, o1;
; #pragma unroll
;                 for (int j = 0; j < 4; ++j) { o0[j] = sigmoid_f(acc[ai][0][m][0][j] * rs) * a0[j] + sigmoid_f(acc[ai][1][m][0][j] * rs) * m0[j];
;                                               o1[j] = sigmoid_f(acc[ai][0][m][1][j] * rs) * a1[j] + sigmoid_f(acc[ai][1][m][1][j] * rs) * m1[j]; }
;                 *(u32x4*)(MRG + (size_t)(rowb + ai * 128 + m * 16) * 2048 + col0) = pack8(o0, o1);
	v_mul_f32_e32 v30, 0xbfb8aa3b, v30
	v_exp_f32_e32 v30, v30
	v_add_f32_e32 v27, 1.0, v27
	v_rcp_f32_e32 v27, v27
	v_mul_f32_e32 v23, v23, v38
	v_add_f32_e32 v16, 1.0, v30
	v_rcp_f32_e32 v22, v17
	v_add_f32_e32 v17, 1.0, v28
	v_mul_f32_e32 v23, 0xbfb8aa3b, v23
	v_mul_f32_e32 v19, v19, v38
	v_rcp_f32_e32 v16, v16
	v_rcp_f32_e32 v17, v17
	v_lshlrev_b32_e32 v30, 16, v73
	v_and_b32_e32 v31, 0xffff0000, v73
	v_exp_f32_e32 v23, v23
	v_mul_f32_e32 v19, 0xbfb8aa3b, v19
	v_pk_mul_f32 v[26:27], v[26:27], v[30:31]
	v_exp_f32_e32 v30, v19
	v_lshlrev_b32_e32 v28, 16, v77
	v_and_b32_e32 v29, 0xffff0000, v77
	v_pk_fma_f32 v[26:27], v[16:17], v[28:29], v[26:27]
	v_add_f32_e32 v16, 1.0, v23
	v_rcp_f32_e32 v19, v16
	v_add_f32_e32 v16, 1.0, v30
	v_rcp_f32_e32 v23, v16
	v_lshlrev_b32_e32 v28, 16, v75
	v_and_b32_e32 v29, 0xffff0000, v75
	v_lshlrev_b32_e32 v16, 16, v79
	v_and_b32_e32 v17, 0xffff0000, v79
	v_pk_mul_f32 v[22:23], v[22:23], v[28:29]
	s_nop 0
	v_pk_fma_f32 v[22:23], v[18:19], v[16:17], v[22:23]
	v_cvt_pk_bf16_f32 v18, v20, v21
	v_fmamk_f32 v20, v227, 0x3a000000, v226
	v_mul_f32_e32 v21, 0x4b800000, v20
	v_cmp_gt_f32_e32 vcc, s56, v20
	v_cvt_pk_bf16_f32 v19, v22, v23
	v_cvt_pk_bf16_f32 v16, v24, v25
	v_cndmask_b32_e32 v20, v20, v21, vcc
	v_rsq_f32_e32 v22, v20
	v_lshlrev_b64 v[20:21], 12, v[90:91]
	v_lshl_add_u64 v[20:21], s[12:13], 0, v[20:21]
	v_cvt_pk_bf16_f32 v17, v26, v27
	v_mul_f32_e32 v23, 0x45800000, v22
	v_cndmask_b32_e32 v22, v22, v23, vcc
	v_mul_f32_e32 v4, v4, v22
	v_mul_f32_e32 v0, v0, v22
	v_lshl_add_u64 v[20:21], v[20:21], 0, v[112:113]
	v_mul_f32_e32 v4, 0xbfb8aa3b, v4
	v_mul_f32_e32 v0, 0xbfb8aa3b, v0
	global_store_dwordx4 v[20:21], v[16:19], off
	v_exp_f32_e32 v4, v4
	v_mul_f32_e32 v12, v12, v22
	v_exp_f32_e32 v16, v0
	v_mul_f32_e32 v8, v8, v22
	v_mul_f32_e32 v13, v13, v22
	v_mul_f32_e32 v9, v9, v22
	v_mul_f32_e32 v12, 0xbfb8aa3b, v12
	v_mul_f32_e32 v8, 0xbfb8aa3b, v8
	v_mul_f32_e32 v13, 0xbfb8aa3b, v13
	v_mul_f32_e32 v9, 0xbfb8aa3b, v9
	v_exp_f32_e32 v12, v12
	v_exp_f32_e32 v23, v8
	v_add_f32_e32 v0, 1.0, v4
	v_add_f32_e32 v4, 1.0, v16
	v_exp_f32_e32 v13, v13
	v_exp_f32_e32 v16, v9
	v_add_f32_e32 v8, 1.0, v12
	v_add_f32_e32 v12, 1.0, v23
	v_add_f32_e32 v9, 1.0, v13
	v_add_f32_e32 v13, 1.0, v16
	v_rcp_f32_e32 v12, v12
	v_rcp_f32_e32 v13, v13
	v_mul_f32_e32 v5, v5, v22
	v_mul_f32_e32 v1, v1, v22
	s_waitcnt vmcnt(0)
	v_lshlrev_b32_e32 v18, 16, v64
	v_and_b32_e32 v19, 0xffff0000, v64
	v_mul_f32_e32 v5, 0xbfb8aa3b, v5
	v_mul_f32_e32 v1, 0xbfb8aa3b, v1
	v_pk_mul_f32 v[12:13], v[12:13], v[18:19]
	v_exp_f32_e32 v5, v5
	v_exp_f32_e32 v18, v1
	v_rcp_f32_e32 v8, v8
	v_rcp_f32_e32 v9, v9
	v_add_f32_e32 v1, 1.0, v5
	v_add_f32_e32 v5, 1.0, v18
	v_rcp_f32_e32 v4, v4
	v_rcp_f32_e32 v5, v5
	v_mul_f32_e32 v10, v10, v22
	v_rcp_f32_e32 v0, v0
	v_rcp_f32_e32 v1, v1
	v_mul_f32_e32 v10, 0xbfb8aa3b, v10
	v_mul_f32_e32 v6, v6, v22
	v_lshlrev_b32_e32 v16, 16, v68
	v_and_b32_e32 v17, 0xffff0000, v68
	v_exp_f32_e32 v10, v10
	v_mul_f32_e32 v6, 0xbfb8aa3b, v6
	v_pk_fma_f32 v[8:9], v[8:9], v[16:17], v[12:13]
	v_lshlrev_b32_e32 v16, 16, v66
	v_and_b32_e32 v17, 0xffff0000, v66
	v_exp_f32_e32 v6, v6
	v_mul_f32_e32 v2, v2, v22
	v_lshlrev_b32_e32 v12, 16, v70
	v_and_b32_e32 v13, 0xffff0000, v70
	v_pk_mul_f32 v[4:5], v[4:5], v[16:17]
	v_mul_f32_e32 v2, 0xbfb8aa3b, v2
	v_pk_fma_f32 v[4:5], v[0:1], v[12:13], v[4:5]
	v_exp_f32_e32 v12, v2
	v_add_f32_e32 v1, 1.0, v10
	v_rcp_f32_e32 v10, v1
	v_add_f32_e32 v1, 1.0, v6
	v_mul_f32_e32 v6, v15, v22
	v_mul_f32_e32 v6, 0xbfb8aa3b, v6
	v_rcp_f32_e32 v2, v1
	v_add_f32_e32 v1, 1.0, v12
	v_exp_f32_e32 v12, v6
	v_mul_f32_e32 v6, v11, v22
	v_mul_f32_e32 v6, 0xbfb8aa3b, v6
	v_exp_f32_e32 v11, v6
	v_mul_f32_e32 v14, v14, v22
	v_mul_f32_e32 v14, 0xbfb8aa3b, v14
	v_exp_f32_e32 v14, v14
	v_add_f32_e32 v11, 1.0, v11
	v_rcp_f32_e32 v11, v11
	v_mul_f32_e32 v7, v7, v22
	v_add_f32_e32 v0, 1.0, v14
	v_rcp_f32_e32 v6, v1
	v_add_f32_e32 v1, 1.0, v12
	v_mul_f32_e32 v7, 0xbfb8aa3b, v7
	v_mul_f32_e32 v3, v3, v22
	v_rcp_f32_e32 v0, v0
	v_rcp_f32_e32 v1, v1
	v_lshlrev_b32_e32 v14, 16, v65
	v_and_b32_e32 v15, 0xffff0000, v65
	v_exp_f32_e32 v7, v7
	v_mul_f32_e32 v3, 0xbfb8aa3b, v3
	v_pk_mul_f32 v[10:11], v[10:11], v[14:15]
	v_exp_f32_e32 v14, v3
	v_lshlrev_b32_e32 v12, 16, v69
	v_and_b32_e32 v13, 0xffff0000, v69
	v_pk_fma_f32 v[10:11], v[0:1], v[12:13], v[10:11]
	v_add_f32_e32 v0, 1.0, v7
	v_rcp_f32_e32 v3, v0
	v_add_f32_e32 v0, 1.0, v14
	v_rcp_f32_e32 v7, v0
	v_lshlrev_b32_e32 v12, 16, v67
	v_and_b32_e32 v13, 0xffff0000, v67
	v_lshlrev_b32_e32 v0, 16, v71
	v_and_b32_e32 v1, 0xffff0000, v71
	v_pk_mul_f32 v[6:7], v[6:7], v[12:13]
	s_andn2_b64 vcc, exec, s[6:7]
	v_pk_fma_f32 v[6:7], v[2:3], v[0:1], v[6:7]
	v_cvt_pk_bf16_f32 v2, v4, v5
	v_lshlrev_b64 v[4:5], 12, v[88:89]
	v_lshl_add_u64 v[4:5], s[12:13], 0, v[4:5]
	v_cvt_pk_bf16_f32 v0, v8, v9
	v_cvt_pk_bf16_f32 v1, v10, v11
	v_cvt_pk_bf16_f32 v3, v6, v7
	v_lshl_add_u64 v[4:5], v[4:5], 0, v[112:113]
	s_mov_b64 s[6:7], -1
	global_store_dwordx4 v[4:5], v[0:3], off
	s_cbranch_vccnz .LBB0_1179
	s_andn2_b64 vcc, exec, s[10:11]
	s_cbranch_vccnz .LBB0_1178
	s_barrier
	s_branch .LBB0_1178
